# GEMM K-loops: MFMA order within each 16-MFMA block changed so the two K-steps of each accumulator are adjacent (accumulate chain via SrcC forwarding, per-accumulator order unchanged); otherwise as v67
# speedup vs baseline: 1.0166x; 1.0133x over previous
.LBB0_320:
	s_add_u32 s20, s40, 0xfffc0080
	s_addc_u32 s21, s41, -1
	s_add_i32 s77, 0, 0x10000
	s_cmp_eq_u32 s76, 12
	s_cselect_b32 s59, s49, s21
	s_cselect_b32 s58, s55, s20
	s_cselect_b32 s21, s45, s75
	s_cselect_b32 s20, s73, s74
	s_add_i32 s80, 0, 0x14000
	v_add_u32_e32 v60, s77, v183
	v_add_u32_e32 v168, s80, v183
	ds_read_b128 v[48:51], v60
	ds_read_b128 v[52:55], v60 offset:1024
	ds_read_b128 v[56:59], v60 offset:2048
	ds_read_b128 v[60:63], v60 offset:3072
	ds_read_b128 v[164:167], v168
	ds_read_b128 v[170:173], v168 offset:1024
	ds_read_b128 v[174:177], v168 offset:2048
	ds_read_b128 v[178:181], v168 offset:3072
	v_lshl_add_u64 v[228:229], s[40:41], 0, v[162:163]
	s_add_i32 m0, s57, 0xc000
	ds_read_b128 v[204:207], v202
	ds_read_b128 v[208:211], v202 offset:1024
	ds_read_b128 v[212:215], v202 offset:2048
	ds_read_b128 v[216:219], v202 offset:3072
	ds_read_b128 v[220:223], v202 offset:4096
	ds_read_b128 v[224:227], v202 offset:5120
	ds_read_b128 v[240:243], v202 offset:6144
	ds_read_b128 v[244:247], v202 offset:7168
	global_load_lds_dwordx4 v[228:229], off
	v_lshl_add_u64 v[228:229], s[40:41], 0, v[160:161]
	s_add_i32 m0, s57, 0xe000
	s_nop 0
	global_load_lds_dwordx4 v[228:229], off
	s_waitcnt vmcnt(8)
	s_waitcnt lgkmcnt(0)
	s_setprio 1
	s_barrier
	v_mfma_f32_16x16x32_bf16 v[140:143], v[48:51], v[204:207], v[140:143]
	v_mfma_f32_16x16x32_bf16 v[140:143], v[52:55], v[208:211], v[140:143]
	v_mfma_f32_16x16x32_bf16 v[136:139], v[56:59], v[204:207], v[136:139]
	v_mfma_f32_16x16x32_bf16 v[136:139], v[60:63], v[208:211], v[136:139]
	v_mfma_f32_16x16x32_bf16 v[124:127], v[48:51], v[212:215], v[124:127]
	v_mfma_f32_16x16x32_bf16 v[124:127], v[52:55], v[216:219], v[124:127]
	v_mfma_f32_16x16x32_bf16 v[120:123], v[56:59], v[212:215], v[120:123]
	v_mfma_f32_16x16x32_bf16 v[120:123], v[60:63], v[216:219], v[120:123]
	v_mfma_f32_16x16x32_bf16 v[108:111], v[48:51], v[220:223], v[108:111]
	v_mfma_f32_16x16x32_bf16 v[108:111], v[52:55], v[224:227], v[108:111]
	v_mfma_f32_16x16x32_bf16 v[104:107], v[56:59], v[220:223], v[104:107]
	v_mfma_f32_16x16x32_bf16 v[104:107], v[60:63], v[224:227], v[104:107]
	v_mfma_f32_16x16x32_bf16 v[92:95], v[48:51], v[240:243], v[92:95]
	v_mfma_f32_16x16x32_bf16 v[92:95], v[52:55], v[244:247], v[92:95]
	v_mfma_f32_16x16x32_bf16 v[88:91], v[56:59], v[240:243], v[88:91]
	v_mfma_f32_16x16x32_bf16 v[88:91], v[60:63], v[244:247], v[88:91]
	v_mfma_f32_16x16x32_bf16 v[132:135], v[164:167], v[204:207], v[132:135]
	v_mfma_f32_16x16x32_bf16 v[132:135], v[170:173], v[208:211], v[132:135]
	v_mfma_f32_16x16x32_bf16 v[128:131], v[174:177], v[204:207], v[128:131]
	v_mfma_f32_16x16x32_bf16 v[128:131], v[178:181], v[208:211], v[128:131]
	v_mfma_f32_16x16x32_bf16 v[116:119], v[164:167], v[212:215], v[116:119]
	v_mfma_f32_16x16x32_bf16 v[116:119], v[170:173], v[216:219], v[116:119]
	v_mfma_f32_16x16x32_bf16 v[112:115], v[174:177], v[212:215], v[112:115]
	v_mfma_f32_16x16x32_bf16 v[112:115], v[178:181], v[216:219], v[112:115]
	v_mfma_f32_16x16x32_bf16 v[100:103], v[164:167], v[220:223], v[100:103]
	v_mfma_f32_16x16x32_bf16 v[100:103], v[170:173], v[224:227], v[100:103]
	v_mfma_f32_16x16x32_bf16 v[96:99], v[174:177], v[220:223], v[96:99]
	v_mfma_f32_16x16x32_bf16 v[96:99], v[178:181], v[224:227], v[96:99]
	v_mfma_f32_16x16x32_bf16 v[84:87], v[164:167], v[240:243], v[84:87]
	v_mfma_f32_16x16x32_bf16 v[84:87], v[170:173], v[244:247], v[84:87]
	v_mfma_f32_16x16x32_bf16 v[80:83], v[174:177], v[240:243], v[80:83]
	v_mfma_f32_16x16x32_bf16 v[80:83], v[178:181], v[244:247], v[80:83]
	s_barrier
	s_setprio 0
	s_add_i32 s77, s77, s62
	v_lshl_add_u64 v[228:229], s[20:21], 0, v[146:147]
	s_mov_b32 m0, s77
	ds_read_b128 v[204:207], v202 offset:16384
	ds_read_b128 v[208:211], v202 offset:17408
	ds_read_b128 v[212:215], v202 offset:18432
	ds_read_b128 v[216:219], v202 offset:19456
	ds_read_b128 v[220:223], v202 offset:20480
	ds_read_b128 v[224:227], v202 offset:21504
	ds_read_b128 v[240:243], v202 offset:22528
	ds_read_b128 v[244:247], v202 offset:23552
	global_load_lds_dwordx4 v[228:229], off
	s_add_i32 m0, s77, 0x2000
	s_add_u32 s78, s20, 0x40000
	v_lshl_add_u64 v[230:231], s[20:21], 0, v[150:151]
	s_addc_u32 s79, s21, 0
	s_add_i32 s77, s80, s62
	global_load_lds_dwordx4 v[230:231], off
	v_lshl_add_u64 v[232:233], s[78:79], 0, v[146:147]
	s_mov_b32 m0, s77
	v_lshl_add_u64 v[234:235], s[58:59], 0, v[148:149]
	global_load_lds_dwordx4 v[232:233], off
	v_lshl_add_u64 v[232:233], s[78:79], 0, v[150:151]
	s_add_i32 m0, s77, 0x2000
	s_nop 0
	global_load_lds_dwordx4 v[232:233], off
	v_lshl_add_u64 v[232:233], s[58:59], 0, v[144:145]
	s_mov_b32 m0, s57
	s_nop 0
	global_load_lds_dwordx4 v[232:233], off
	s_mov_b32 m0, s65
	s_nop 0
	global_load_lds_dwordx4 v[234:235], off
	s_waitcnt vmcnt(8)
	s_waitcnt lgkmcnt(0)
	s_setprio 1
	s_barrier
	v_mfma_f32_16x16x32_bf16 v[76:79], v[48:51], v[204:207], v[76:79]
	v_mfma_f32_16x16x32_bf16 v[76:79], v[52:55], v[208:211], v[76:79]
	v_mfma_f32_16x16x32_bf16 v[72:75], v[56:59], v[204:207], v[72:75]
	v_mfma_f32_16x16x32_bf16 v[72:75], v[60:63], v[208:211], v[72:75]
	v_mfma_f32_16x16x32_bf16 v[44:47], v[48:51], v[212:215], v[44:47]
	v_mfma_f32_16x16x32_bf16 v[44:47], v[52:55], v[216:219], v[44:47]
	v_mfma_f32_16x16x32_bf16 v[40:43], v[56:59], v[212:215], v[40:43]
	v_mfma_f32_16x16x32_bf16 v[40:43], v[60:63], v[216:219], v[40:43]
	v_mfma_f32_16x16x32_bf16 v[28:31], v[48:51], v[220:223], v[28:31]
	v_mfma_f32_16x16x32_bf16 v[28:31], v[52:55], v[224:227], v[28:31]
	v_mfma_f32_16x16x32_bf16 v[24:27], v[56:59], v[220:223], v[24:27]
	v_mfma_f32_16x16x32_bf16 v[24:27], v[60:63], v[224:227], v[24:27]
	v_mfma_f32_16x16x32_bf16 v[12:15], v[48:51], v[240:243], v[12:15]
	v_mfma_f32_16x16x32_bf16 v[12:15], v[52:55], v[244:247], v[12:15]
	v_mfma_f32_16x16x32_bf16 v[8:11], v[56:59], v[240:243], v[8:11]
	v_mfma_f32_16x16x32_bf16 v[8:11], v[60:63], v[244:247], v[8:11]
	v_mfma_f32_16x16x32_bf16 v[36:39], v[164:167], v[212:215], v[36:39]
	v_mfma_f32_16x16x32_bf16 v[36:39], v[170:173], v[216:219], v[36:39]
	v_mfma_f32_16x16x32_bf16 v[32:35], v[174:177], v[212:215], v[32:35]
	v_mfma_f32_16x16x32_bf16 v[32:35], v[178:181], v[216:219], v[32:35]
	v_mfma_f32_16x16x32_bf16 v[20:23], v[164:167], v[220:223], v[20:23]
	v_mfma_f32_16x16x32_bf16 v[20:23], v[170:173], v[224:227], v[20:23]
	v_mfma_f32_16x16x32_bf16 v[16:19], v[174:177], v[220:223], v[16:19]
	v_mfma_f32_16x16x32_bf16 v[16:19], v[178:181], v[224:227], v[16:19]
	v_mfma_f32_16x16x32_bf16 v[4:7], v[164:167], v[240:243], v[4:7]
	v_mfma_f32_16x16x32_bf16 v[4:7], v[170:173], v[244:247], v[4:7]
	v_mfma_f32_16x16x32_bf16 v[0:3], v[174:177], v[240:243], v[0:3]
	v_mfma_f32_16x16x32_bf16 v[0:3], v[178:181], v[244:247], v[0:3]
	v_mfma_f32_16x16x32_bf16 v[48:51], v[164:167], v[204:207], v[68:71]
	v_mfma_f32_16x16x32_bf16 v[48:51], v[170:173], v[208:211], v[48:51]
	v_mfma_f32_16x16x32_bf16 v[52:55], v[174:177], v[204:207], v[64:67]
	v_mfma_f32_16x16x32_bf16 v[52:55], v[178:181], v[208:211], v[52:55]
	s_barrier
	s_setprio 0
	s_add_i32 s77, 0, 0x18000
	s_add_i32 s78, 0, 0x1c000
	v_add_u32_e32 v68, s77, v183
	v_add_u32_e32 v168, s78, v183
	ds_read_b128 v[56:59], v68
	ds_read_b128 v[60:63], v68 offset:1024
	ds_read_b128 v[64:67], v68 offset:2048
	ds_read_b128 v[68:71], v68 offset:3072
	ds_read_b128 v[164:167], v168
	ds_read_b128 v[170:173], v168 offset:1024
	ds_read_b128 v[174:177], v168 offset:2048
	ds_read_b128 v[178:181], v168 offset:3072
	s_add_u32 s58, s58, 0x40000
	s_addc_u32 s59, s59, 0
	s_mov_b32 m0, s66
	v_lshl_add_u64 v[236:237], s[58:59], 0, v[144:145]
	ds_read_b128 v[204:207], v202 offset:32768
	ds_read_b128 v[208:211], v202 offset:33792
	ds_read_b128 v[212:215], v202 offset:34816
	ds_read_b128 v[216:219], v202 offset:35840
	ds_read_b128 v[220:223], v202 offset:36864
	ds_read_b128 v[224:227], v202 offset:37888
	ds_read_b128 v[240:243], v202 offset:38912
	ds_read_b128 v[244:247], v202 offset:39936
	global_load_lds_dwordx4 v[236:237], off
	v_lshl_add_u64 v[236:237], s[58:59], 0, v[148:149]
	s_mov_b32 m0, s67
	s_nop 0
	global_load_lds_dwordx4 v[236:237], off
	s_waitcnt vmcnt(8)
	s_waitcnt lgkmcnt(0)
	s_setprio 1
	s_barrier
	v_mfma_f32_16x16x32_bf16 v[140:143], v[56:59], v[204:207], v[140:143]
	v_mfma_f32_16x16x32_bf16 v[140:143], v[60:63], v[208:211], v[140:143]
	v_mfma_f32_16x16x32_bf16 v[136:139], v[64:67], v[204:207], v[136:139]
	v_mfma_f32_16x16x32_bf16 v[136:139], v[68:71], v[208:211], v[136:139]
	v_mfma_f32_16x16x32_bf16 v[124:127], v[56:59], v[212:215], v[124:127]
	v_mfma_f32_16x16x32_bf16 v[124:127], v[60:63], v[216:219], v[124:127]
	v_mfma_f32_16x16x32_bf16 v[120:123], v[64:67], v[212:215], v[120:123]
	v_mfma_f32_16x16x32_bf16 v[120:123], v[68:71], v[216:219], v[120:123]
	v_mfma_f32_16x16x32_bf16 v[108:111], v[56:59], v[220:223], v[108:111]
	v_mfma_f32_16x16x32_bf16 v[108:111], v[60:63], v[224:227], v[108:111]
	v_mfma_f32_16x16x32_bf16 v[104:107], v[64:67], v[220:223], v[104:107]
	v_mfma_f32_16x16x32_bf16 v[104:107], v[68:71], v[224:227], v[104:107]
	v_mfma_f32_16x16x32_bf16 v[92:95], v[56:59], v[240:243], v[92:95]
	v_mfma_f32_16x16x32_bf16 v[92:95], v[60:63], v[244:247], v[92:95]
	v_mfma_f32_16x16x32_bf16 v[88:91], v[64:67], v[240:243], v[88:91]
	v_mfma_f32_16x16x32_bf16 v[88:91], v[68:71], v[244:247], v[88:91]
	v_mfma_f32_16x16x32_bf16 v[132:135], v[164:167], v[204:207], v[132:135]
	v_mfma_f32_16x16x32_bf16 v[132:135], v[170:173], v[208:211], v[132:135]
	v_mfma_f32_16x16x32_bf16 v[128:131], v[174:177], v[204:207], v[128:131]
	v_mfma_f32_16x16x32_bf16 v[128:131], v[178:181], v[208:211], v[128:131]
	v_mfma_f32_16x16x32_bf16 v[116:119], v[164:167], v[212:215], v[116:119]
	v_mfma_f32_16x16x32_bf16 v[116:119], v[170:173], v[216:219], v[116:119]
	v_mfma_f32_16x16x32_bf16 v[112:115], v[174:177], v[212:215], v[112:115]
	v_mfma_f32_16x16x32_bf16 v[112:115], v[178:181], v[216:219], v[112:115]
	v_mfma_f32_16x16x32_bf16 v[100:103], v[164:167], v[220:223], v[100:103]
	v_mfma_f32_16x16x32_bf16 v[100:103], v[170:173], v[224:227], v[100:103]
	v_mfma_f32_16x16x32_bf16 v[96:99], v[174:177], v[220:223], v[96:99]
	v_mfma_f32_16x16x32_bf16 v[96:99], v[178:181], v[224:227], v[96:99]
	v_mfma_f32_16x16x32_bf16 v[84:87], v[164:167], v[240:243], v[84:87]
	v_mfma_f32_16x16x32_bf16 v[84:87], v[170:173], v[244:247], v[84:87]
	v_mfma_f32_16x16x32_bf16 v[80:83], v[174:177], v[240:243], v[80:83]
	v_mfma_f32_16x16x32_bf16 v[80:83], v[178:181], v[244:247], v[80:83]
	s_barrier
	s_setprio 0
	s_add_i32 s58, s77, s62
	v_lshl_add_u64 v[228:229], v[228:229], 0, s[36:37]
	s_mov_b32 m0, s58
	ds_read_b128 v[204:207], v202 offset:49152
	ds_read_b128 v[208:211], v202 offset:50176
	ds_read_b128 v[212:215], v202 offset:51200
	ds_read_b128 v[216:219], v202 offset:52224
	ds_read_b128 v[220:223], v202 offset:53248
	ds_read_b128 v[224:227], v202 offset:54272
	ds_read_b128 v[240:243], v202 offset:55296
	ds_read_b128 v[244:247], v202 offset:56320
	global_load_lds_dwordx4 v[228:229], off
	s_add_i32 m0, s58, 0x2000
	s_add_u32 s20, s20, 0x40080
	v_lshl_add_u64 v[228:229], v[230:231], 0, s[36:37]
	s_addc_u32 s21, s21, 0
	s_add_i32 s58, s78, s62
	global_load_lds_dwordx4 v[228:229], off
	v_lshl_add_u64 v[228:229], s[20:21], 0, v[146:147]
	s_mov_b32 m0, s58
	s_nop 0
	global_load_lds_dwordx4 v[228:229], off
	v_lshl_add_u64 v[228:229], s[20:21], 0, v[150:151]
	s_add_i32 m0, s58, 0x2000
	s_nop 0
	global_load_lds_dwordx4 v[228:229], off
	v_lshl_add_u64 v[228:229], v[232:233], 0, s[36:37]
	s_mov_b32 m0, s69
	s_nop 0
	global_load_lds_dwordx4 v[228:229], off
	v_lshl_add_u64 v[228:229], v[234:235], 0, s[36:37]
	s_mov_b32 m0, s70
	s_nop 0
	global_load_lds_dwordx4 v[228:229], off
	s_waitcnt vmcnt(8)
	s_waitcnt lgkmcnt(0)
	s_setprio 1
	s_barrier
	v_mfma_f32_16x16x32_bf16 v[76:79], v[56:59], v[204:207], v[76:79]
	v_mfma_f32_16x16x32_bf16 v[76:79], v[60:63], v[208:211], v[76:79]
	v_mfma_f32_16x16x32_bf16 v[72:75], v[64:67], v[204:207], v[72:75]
	v_mfma_f32_16x16x32_bf16 v[72:75], v[68:71], v[208:211], v[72:75]
	v_mfma_f32_16x16x32_bf16 v[44:47], v[56:59], v[212:215], v[44:47]
	v_mfma_f32_16x16x32_bf16 v[44:47], v[60:63], v[216:219], v[44:47]
	v_mfma_f32_16x16x32_bf16 v[40:43], v[64:67], v[212:215], v[40:43]
	v_mfma_f32_16x16x32_bf16 v[40:43], v[68:71], v[216:219], v[40:43]
	v_mfma_f32_16x16x32_bf16 v[28:31], v[56:59], v[220:223], v[28:31]
	v_mfma_f32_16x16x32_bf16 v[28:31], v[60:63], v[224:227], v[28:31]
	v_mfma_f32_16x16x32_bf16 v[24:27], v[64:67], v[220:223], v[24:27]
	v_mfma_f32_16x16x32_bf16 v[24:27], v[68:71], v[224:227], v[24:27]
	v_mfma_f32_16x16x32_bf16 v[12:15], v[56:59], v[240:243], v[12:15]
	v_mfma_f32_16x16x32_bf16 v[12:15], v[60:63], v[244:247], v[12:15]
	v_mfma_f32_16x16x32_bf16 v[8:11], v[64:67], v[240:243], v[8:11]
	v_mfma_f32_16x16x32_bf16 v[8:11], v[68:71], v[244:247], v[8:11]
	v_mfma_f32_16x16x32_bf16 v[48:51], v[164:167], v[204:207], v[48:51]
	v_mfma_f32_16x16x32_bf16 v[68:71], v[170:173], v[208:211], v[48:51]
	v_mfma_f32_16x16x32_bf16 v[48:51], v[174:177], v[204:207], v[52:55]
	v_mfma_f32_16x16x32_bf16 v[36:39], v[164:167], v[212:215], v[36:39]
	v_mfma_f32_16x16x32_bf16 v[32:35], v[174:177], v[212:215], v[32:35]
	v_mfma_f32_16x16x32_bf16 v[20:23], v[164:167], v[220:223], v[20:23]
	v_mfma_f32_16x16x32_bf16 v[16:19], v[174:177], v[220:223], v[16:19]
	v_mfma_f32_16x16x32_bf16 v[4:7], v[164:167], v[240:243], v[4:7]
	v_mfma_f32_16x16x32_bf16 v[0:3], v[174:177], v[240:243], v[0:3]
	v_mfma_f32_16x16x32_bf16 v[64:67], v[178:181], v[208:211], v[48:51]
	v_mfma_f32_16x16x32_bf16 v[36:39], v[170:173], v[216:219], v[36:39]
	v_mfma_f32_16x16x32_bf16 v[32:35], v[178:181], v[216:219], v[32:35]
	v_mfma_f32_16x16x32_bf16 v[20:23], v[170:173], v[224:227], v[20:23]
	v_mfma_f32_16x16x32_bf16 v[16:19], v[178:181], v[224:227], v[16:19]
	v_mfma_f32_16x16x32_bf16 v[4:7], v[170:173], v[244:247], v[4:7]
	v_mfma_f32_16x16x32_bf16 v[0:3], v[178:181], v[244:247], v[0:3]
	s_barrier
	s_setprio 0
	s_add_i32 s76, s76, 2
	s_add_u32 s74, s74, 0x100
	s_addc_u32 s75, s75, 0
	s_add_u32 s40, s40, 0x100
	s_addc_u32 s41, s41, 0
	s_cmp_gt_u32 s76, 13
	s_cbranch_scc0 .LBB0_320
	s_and_b64 vcc, exec, s[42:43]
	s_cbranch_vccz .LBB0_323
	s_barrier

.LBB0_478:
	s_add_u32 s20, s40, 0xfffc0080
	s_addc_u32 s21, s41, -1
	s_add_i32 s65, 0, 0x10000
	s_cmp_eq_u32 s64, 12
	s_cselect_b32 s43, s15, s21
	s_cselect_b32 s42, s45, s20
	v_add_u32_e32 v167, s65, v149
	s_cselect_b32 s21, s13, s63
	s_cselect_b32 s20, s61, s62
	s_add_i32 s68, 0, 0x14000
	ds_read_b128 v[140:143], v167
	ds_read_b128 v[144:147], v167 offset:1024
	ds_read_b128 v[170:173], v167 offset:2048
	ds_read_b128 v[174:177], v167 offset:3072
	v_add_u32_e32 v167, s68, v149
	ds_read_b128 v[178:181], v167
	ds_read_b128 v[182:185], v167 offset:1024
	ds_read_b128 v[186:189], v167 offset:2048
	ds_read_b128 v[190:193], v167 offset:3072
	v_lshl_add_u64 v[226:227], s[40:41], 0, v[138:139]
	s_add_i32 m0, s53, 0xc000
	ds_read_b128 v[194:197], v166
	ds_read_b128 v[198:201], v166 offset:1024
	ds_read_b128 v[202:205], v166 offset:2048
	ds_read_b128 v[206:209], v166 offset:3072
	ds_read_b128 v[210:213], v166 offset:4096
	ds_read_b128 v[214:217], v166 offset:5120
	ds_read_b128 v[218:221], v166 offset:6144
	ds_read_b128 v[222:225], v166 offset:7168
	global_load_lds_dwordx4 v[226:227], off
	v_lshl_add_u64 v[226:227], s[40:41], 0, v[136:137]
	s_add_i32 m0, s53, 0xe000
	s_nop 0
	global_load_lds_dwordx4 v[226:227], off
	s_waitcnt vmcnt(8)
	s_waitcnt lgkmcnt(0)
	s_setprio 1
	s_barrier
	v_mfma_f32_16x16x32_bf16 v[124:127], v[140:143], v[194:197], v[124:127]
	v_mfma_f32_16x16x32_bf16 v[124:127], v[144:147], v[198:201], v[124:127]
	v_mfma_f32_16x16x32_bf16 v[120:123], v[170:173], v[194:197], v[120:123]
	v_mfma_f32_16x16x32_bf16 v[120:123], v[174:177], v[198:201], v[120:123]
	v_mfma_f32_16x16x32_bf16 v[108:111], v[140:143], v[202:205], v[108:111]
	v_mfma_f32_16x16x32_bf16 v[108:111], v[144:147], v[206:209], v[108:111]
	v_mfma_f32_16x16x32_bf16 v[104:107], v[170:173], v[202:205], v[104:107]
	v_mfma_f32_16x16x32_bf16 v[104:107], v[174:177], v[206:209], v[104:107]
	v_mfma_f32_16x16x32_bf16 v[92:95], v[140:143], v[210:213], v[92:95]
	v_mfma_f32_16x16x32_bf16 v[92:95], v[144:147], v[214:217], v[92:95]
	v_mfma_f32_16x16x32_bf16 v[88:91], v[170:173], v[210:213], v[88:91]
	v_mfma_f32_16x16x32_bf16 v[88:91], v[174:177], v[214:217], v[88:91]
	v_mfma_f32_16x16x32_bf16 v[76:79], v[140:143], v[218:221], v[76:79]
	v_mfma_f32_16x16x32_bf16 v[76:79], v[144:147], v[222:225], v[76:79]
	v_mfma_f32_16x16x32_bf16 v[72:75], v[170:173], v[218:221], v[72:75]
	v_mfma_f32_16x16x32_bf16 v[72:75], v[174:177], v[222:225], v[72:75]
	v_mfma_f32_16x16x32_bf16 v[116:119], v[178:181], v[194:197], v[116:119]
	v_mfma_f32_16x16x32_bf16 v[116:119], v[182:185], v[198:201], v[116:119]
	v_mfma_f32_16x16x32_bf16 v[112:115], v[186:189], v[194:197], v[112:115]
	v_mfma_f32_16x16x32_bf16 v[112:115], v[190:193], v[198:201], v[112:115]
	v_mfma_f32_16x16x32_bf16 v[100:103], v[178:181], v[202:205], v[100:103]
	v_mfma_f32_16x16x32_bf16 v[100:103], v[182:185], v[206:209], v[100:103]
	v_mfma_f32_16x16x32_bf16 v[96:99], v[186:189], v[202:205], v[96:99]
	v_mfma_f32_16x16x32_bf16 v[96:99], v[190:193], v[206:209], v[96:99]
	v_mfma_f32_16x16x32_bf16 v[84:87], v[178:181], v[210:213], v[84:87]
	v_mfma_f32_16x16x32_bf16 v[84:87], v[182:185], v[214:217], v[84:87]
	v_mfma_f32_16x16x32_bf16 v[80:83], v[186:189], v[210:213], v[80:83]
	v_mfma_f32_16x16x32_bf16 v[80:83], v[190:193], v[214:217], v[80:83]
	v_mfma_f32_16x16x32_bf16 v[68:71], v[178:181], v[218:221], v[68:71]
	v_mfma_f32_16x16x32_bf16 v[68:71], v[182:185], v[222:225], v[68:71]
	v_mfma_f32_16x16x32_bf16 v[64:67], v[186:189], v[218:221], v[64:67]
	v_mfma_f32_16x16x32_bf16 v[64:67], v[190:193], v[222:225], v[64:67]
	s_barrier
	s_setprio 0
	s_add_i32 s65, s65, s50
	v_lshl_add_u64 v[226:227], s[20:21], 0, v[132:133]
	s_mov_b32 m0, s65
	ds_read_b128 v[194:197], v166 offset:16384
	ds_read_b128 v[198:201], v166 offset:17408
	ds_read_b128 v[202:205], v166 offset:18432
	ds_read_b128 v[206:209], v166 offset:19456
	ds_read_b128 v[210:213], v166 offset:20480
	ds_read_b128 v[214:217], v166 offset:21504
	ds_read_b128 v[218:221], v166 offset:22528
	ds_read_b128 v[222:225], v166 offset:23552
	global_load_lds_dwordx4 v[226:227], off
	s_add_i32 m0, s65, 0x2000
	s_add_u32 s66, s20, 0x40000
	v_lshl_add_u64 v[228:229], s[20:21], 0, v[128:129]
	s_addc_u32 s67, s21, 0
	s_add_i32 s65, s68, s50
	global_load_lds_dwordx4 v[228:229], off
	v_lshl_add_u64 v[230:231], s[66:67], 0, v[132:133]
	s_mov_b32 m0, s65
	v_lshl_add_u64 v[232:233], s[42:43], 0, v[130:131]
	global_load_lds_dwordx4 v[230:231], off
	v_lshl_add_u64 v[230:231], s[66:67], 0, v[128:129]
	s_add_i32 m0, s65, 0x2000
	s_nop 0
	global_load_lds_dwordx4 v[230:231], off
	v_lshl_add_u64 v[230:231], s[42:43], 0, v[134:135]
	s_mov_b32 m0, s53
	s_nop 0
	global_load_lds_dwordx4 v[230:231], off
	s_mov_b32 m0, s54
	s_nop 0
	global_load_lds_dwordx4 v[232:233], off
	s_waitcnt vmcnt(8)
	s_waitcnt lgkmcnt(0)
	s_setprio 1
	s_barrier
	v_mfma_f32_16x16x32_bf16 v[60:63], v[140:143], v[194:197], v[60:63]
	v_mfma_f32_16x16x32_bf16 v[60:63], v[144:147], v[198:201], v[60:63]
	v_mfma_f32_16x16x32_bf16 v[56:59], v[170:173], v[194:197], v[56:59]
	v_mfma_f32_16x16x32_bf16 v[56:59], v[174:177], v[198:201], v[56:59]
	v_mfma_f32_16x16x32_bf16 v[44:47], v[140:143], v[202:205], v[44:47]
	v_mfma_f32_16x16x32_bf16 v[44:47], v[144:147], v[206:209], v[44:47]
	v_mfma_f32_16x16x32_bf16 v[40:43], v[170:173], v[202:205], v[40:43]
	v_mfma_f32_16x16x32_bf16 v[40:43], v[174:177], v[206:209], v[40:43]
	v_mfma_f32_16x16x32_bf16 v[28:31], v[140:143], v[210:213], v[28:31]
	v_mfma_f32_16x16x32_bf16 v[28:31], v[144:147], v[214:217], v[28:31]
	v_mfma_f32_16x16x32_bf16 v[24:27], v[170:173], v[210:213], v[24:27]
	v_mfma_f32_16x16x32_bf16 v[24:27], v[174:177], v[214:217], v[24:27]
	v_mfma_f32_16x16x32_bf16 v[12:15], v[140:143], v[218:221], v[12:15]
	v_mfma_f32_16x16x32_bf16 v[12:15], v[144:147], v[222:225], v[12:15]
	v_mfma_f32_16x16x32_bf16 v[8:11], v[170:173], v[218:221], v[8:11]
	v_mfma_f32_16x16x32_bf16 v[8:11], v[174:177], v[222:225], v[8:11]
	v_mfma_f32_16x16x32_bf16 v[52:55], v[178:181], v[194:197], v[52:55]
	v_mfma_f32_16x16x32_bf16 v[52:55], v[182:185], v[198:201], v[52:55]
	v_mfma_f32_16x16x32_bf16 v[48:51], v[186:189], v[194:197], v[48:51]
	v_mfma_f32_16x16x32_bf16 v[48:51], v[190:193], v[198:201], v[48:51]
	v_mfma_f32_16x16x32_bf16 v[36:39], v[178:181], v[202:205], v[36:39]
	v_mfma_f32_16x16x32_bf16 v[36:39], v[182:185], v[206:209], v[36:39]
	v_mfma_f32_16x16x32_bf16 v[32:35], v[186:189], v[202:205], v[32:35]
	v_mfma_f32_16x16x32_bf16 v[32:35], v[190:193], v[206:209], v[32:35]
	v_mfma_f32_16x16x32_bf16 v[20:23], v[178:181], v[210:213], v[20:23]
	v_mfma_f32_16x16x32_bf16 v[20:23], v[182:185], v[214:217], v[20:23]
	v_mfma_f32_16x16x32_bf16 v[16:19], v[186:189], v[210:213], v[16:19]
	v_mfma_f32_16x16x32_bf16 v[16:19], v[190:193], v[214:217], v[16:19]
	v_mfma_f32_16x16x32_bf16 v[4:7], v[178:181], v[218:221], v[4:7]
	v_mfma_f32_16x16x32_bf16 v[4:7], v[182:185], v[222:225], v[4:7]
	v_mfma_f32_16x16x32_bf16 v[0:3], v[186:189], v[218:221], v[0:3]
	v_mfma_f32_16x16x32_bf16 v[0:3], v[190:193], v[222:225], v[0:3]
	s_barrier
	s_setprio 0
	s_add_i32 s65, 0, 0x18000
	v_add_u32_e32 v167, s65, v149
	s_add_i32 s66, 0, 0x1c000
	ds_read_b128 v[140:143], v167
	ds_read_b128 v[144:147], v167 offset:1024
	ds_read_b128 v[170:173], v167 offset:2048
	ds_read_b128 v[174:177], v167 offset:3072
	v_add_u32_e32 v167, s66, v149
	ds_read_b128 v[178:181], v167
	ds_read_b128 v[182:185], v167 offset:1024
	ds_read_b128 v[186:189], v167 offset:2048
	ds_read_b128 v[190:193], v167 offset:3072
	s_add_u32 s42, s42, 0x40000
	s_addc_u32 s43, s43, 0
	s_mov_b32 m0, s55
	v_lshl_add_u64 v[234:235], s[42:43], 0, v[134:135]
	ds_read_b128 v[194:197], v166 offset:32768
	ds_read_b128 v[198:201], v166 offset:33792
	ds_read_b128 v[202:205], v166 offset:34816
	ds_read_b128 v[206:209], v166 offset:35840
	ds_read_b128 v[210:213], v166 offset:36864
	ds_read_b128 v[214:217], v166 offset:37888
	ds_read_b128 v[218:221], v166 offset:38912
	ds_read_b128 v[222:225], v166 offset:39936
	global_load_lds_dwordx4 v[234:235], off
	v_lshl_add_u64 v[234:235], s[42:43], 0, v[130:131]
	s_mov_b32 m0, s56
	s_nop 0
	global_load_lds_dwordx4 v[234:235], off
	s_waitcnt vmcnt(8)
	s_waitcnt lgkmcnt(0)
	s_setprio 1
	s_barrier
	v_mfma_f32_16x16x32_bf16 v[124:127], v[140:143], v[194:197], v[124:127]
	v_mfma_f32_16x16x32_bf16 v[124:127], v[144:147], v[198:201], v[124:127]
	v_mfma_f32_16x16x32_bf16 v[120:123], v[170:173], v[194:197], v[120:123]
	v_mfma_f32_16x16x32_bf16 v[120:123], v[174:177], v[198:201], v[120:123]
	v_mfma_f32_16x16x32_bf16 v[108:111], v[140:143], v[202:205], v[108:111]
	v_mfma_f32_16x16x32_bf16 v[108:111], v[144:147], v[206:209], v[108:111]
	v_mfma_f32_16x16x32_bf16 v[104:107], v[170:173], v[202:205], v[104:107]
	v_mfma_f32_16x16x32_bf16 v[104:107], v[174:177], v[206:209], v[104:107]
	v_mfma_f32_16x16x32_bf16 v[92:95], v[140:143], v[210:213], v[92:95]
	v_mfma_f32_16x16x32_bf16 v[92:95], v[144:147], v[214:217], v[92:95]
	v_mfma_f32_16x16x32_bf16 v[88:91], v[170:173], v[210:213], v[88:91]
	v_mfma_f32_16x16x32_bf16 v[88:91], v[174:177], v[214:217], v[88:91]
	v_mfma_f32_16x16x32_bf16 v[76:79], v[140:143], v[218:221], v[76:79]
	v_mfma_f32_16x16x32_bf16 v[76:79], v[144:147], v[222:225], v[76:79]
	v_mfma_f32_16x16x32_bf16 v[72:75], v[170:173], v[218:221], v[72:75]
	v_mfma_f32_16x16x32_bf16 v[72:75], v[174:177], v[222:225], v[72:75]
	v_mfma_f32_16x16x32_bf16 v[116:119], v[178:181], v[194:197], v[116:119]
	v_mfma_f32_16x16x32_bf16 v[116:119], v[182:185], v[198:201], v[116:119]
	v_mfma_f32_16x16x32_bf16 v[112:115], v[186:189], v[194:197], v[112:115]
	v_mfma_f32_16x16x32_bf16 v[112:115], v[190:193], v[198:201], v[112:115]
	v_mfma_f32_16x16x32_bf16 v[100:103], v[178:181], v[202:205], v[100:103]
	v_mfma_f32_16x16x32_bf16 v[100:103], v[182:185], v[206:209], v[100:103]
	v_mfma_f32_16x16x32_bf16 v[96:99], v[186:189], v[202:205], v[96:99]
	v_mfma_f32_16x16x32_bf16 v[96:99], v[190:193], v[206:209], v[96:99]
	v_mfma_f32_16x16x32_bf16 v[84:87], v[178:181], v[210:213], v[84:87]
	v_mfma_f32_16x16x32_bf16 v[84:87], v[182:185], v[214:217], v[84:87]
	v_mfma_f32_16x16x32_bf16 v[80:83], v[186:189], v[210:213], v[80:83]
	v_mfma_f32_16x16x32_bf16 v[80:83], v[190:193], v[214:217], v[80:83]
	v_mfma_f32_16x16x32_bf16 v[68:71], v[178:181], v[218:221], v[68:71]
	v_mfma_f32_16x16x32_bf16 v[68:71], v[182:185], v[222:225], v[68:71]
	v_mfma_f32_16x16x32_bf16 v[64:67], v[186:189], v[218:221], v[64:67]
	v_mfma_f32_16x16x32_bf16 v[64:67], v[190:193], v[222:225], v[64:67]
	s_barrier
	s_setprio 0
	s_add_i32 s42, s65, s50
	v_lshl_add_u64 v[226:227], v[226:227], 0, s[36:37]
	s_mov_b32 m0, s42
	ds_read_b128 v[194:197], v166 offset:49152
	ds_read_b128 v[198:201], v166 offset:50176
	ds_read_b128 v[202:205], v166 offset:51200
	ds_read_b128 v[206:209], v166 offset:52224
	ds_read_b128 v[210:213], v166 offset:53248
	ds_read_b128 v[214:217], v166 offset:54272
	ds_read_b128 v[218:221], v166 offset:55296
	ds_read_b128 v[222:225], v166 offset:56320
	global_load_lds_dwordx4 v[226:227], off
	s_add_i32 m0, s42, 0x2000
	s_add_u32 s20, s20, 0x40080
	v_lshl_add_u64 v[226:227], v[228:229], 0, s[36:37]
	s_addc_u32 s21, s21, 0
	s_add_i32 s42, s66, s50
	global_load_lds_dwordx4 v[226:227], off
	v_lshl_add_u64 v[226:227], s[20:21], 0, v[132:133]
	s_mov_b32 m0, s42
	s_nop 0
	global_load_lds_dwordx4 v[226:227], off
	v_lshl_add_u64 v[226:227], s[20:21], 0, v[128:129]
	s_add_i32 m0, s42, 0x2000
	s_nop 0
	global_load_lds_dwordx4 v[226:227], off
	v_lshl_add_u64 v[226:227], v[230:231], 0, s[36:37]
	s_mov_b32 m0, s57
	s_nop 0
	global_load_lds_dwordx4 v[226:227], off
	v_lshl_add_u64 v[226:227], v[232:233], 0, s[36:37]
	s_mov_b32 m0, s58
	s_nop 0
	global_load_lds_dwordx4 v[226:227], off
	s_waitcnt vmcnt(8)
	s_waitcnt lgkmcnt(0)
	s_setprio 1
	s_barrier
	v_mfma_f32_16x16x32_bf16 v[60:63], v[140:143], v[194:197], v[60:63]
	v_mfma_f32_16x16x32_bf16 v[60:63], v[144:147], v[198:201], v[60:63]
	v_mfma_f32_16x16x32_bf16 v[56:59], v[170:173], v[194:197], v[56:59]
	v_mfma_f32_16x16x32_bf16 v[56:59], v[174:177], v[198:201], v[56:59]
	v_mfma_f32_16x16x32_bf16 v[44:47], v[140:143], v[202:205], v[44:47]
	v_mfma_f32_16x16x32_bf16 v[44:47], v[144:147], v[206:209], v[44:47]
	v_mfma_f32_16x16x32_bf16 v[40:43], v[170:173], v[202:205], v[40:43]
	v_mfma_f32_16x16x32_bf16 v[40:43], v[174:177], v[206:209], v[40:43]
	v_mfma_f32_16x16x32_bf16 v[28:31], v[140:143], v[210:213], v[28:31]
	v_mfma_f32_16x16x32_bf16 v[28:31], v[144:147], v[214:217], v[28:31]
	v_mfma_f32_16x16x32_bf16 v[24:27], v[170:173], v[210:213], v[24:27]
	v_mfma_f32_16x16x32_bf16 v[24:27], v[174:177], v[214:217], v[24:27]
	v_mfma_f32_16x16x32_bf16 v[12:15], v[140:143], v[218:221], v[12:15]
	v_mfma_f32_16x16x32_bf16 v[12:15], v[144:147], v[222:225], v[12:15]
	v_mfma_f32_16x16x32_bf16 v[8:11], v[170:173], v[218:221], v[8:11]
	v_mfma_f32_16x16x32_bf16 v[8:11], v[174:177], v[222:225], v[8:11]
	v_mfma_f32_16x16x32_bf16 v[52:55], v[178:181], v[194:197], v[52:55]
	v_mfma_f32_16x16x32_bf16 v[52:55], v[182:185], v[198:201], v[52:55]
	v_mfma_f32_16x16x32_bf16 v[48:51], v[186:189], v[194:197], v[48:51]
	v_mfma_f32_16x16x32_bf16 v[48:51], v[190:193], v[198:201], v[48:51]
	v_mfma_f32_16x16x32_bf16 v[36:39], v[178:181], v[202:205], v[36:39]
	v_mfma_f32_16x16x32_bf16 v[36:39], v[182:185], v[206:209], v[36:39]
	v_mfma_f32_16x16x32_bf16 v[32:35], v[186:189], v[202:205], v[32:35]
	v_mfma_f32_16x16x32_bf16 v[32:35], v[190:193], v[206:209], v[32:35]
	v_mfma_f32_16x16x32_bf16 v[20:23], v[178:181], v[210:213], v[20:23]
	v_mfma_f32_16x16x32_bf16 v[20:23], v[182:185], v[214:217], v[20:23]
	v_mfma_f32_16x16x32_bf16 v[16:19], v[186:189], v[210:213], v[16:19]
	v_mfma_f32_16x16x32_bf16 v[16:19], v[190:193], v[214:217], v[16:19]
	v_mfma_f32_16x16x32_bf16 v[4:7], v[178:181], v[218:221], v[4:7]
	v_mfma_f32_16x16x32_bf16 v[4:7], v[182:185], v[222:225], v[4:7]
	v_mfma_f32_16x16x32_bf16 v[0:3], v[186:189], v[218:221], v[0:3]
	v_mfma_f32_16x16x32_bf16 v[0:3], v[190:193], v[222:225], v[0:3]
	s_barrier
	s_setprio 0
	s_add_i32 s64, s64, 2
	s_add_u32 s62, s62, 0x100
	s_addc_u32 s63, s63, 0
	s_add_u32 s40, s40, 0x100
	s_addc_u32 s41, s41, 0
	s_cmp_gt_u32 s64, 13
	s_cbranch_scc0 .LBB0_478
	s_and_b64 vcc, exec, s[8:9]
	s_cbranch_vccz .LBB0_481
	s_barrier

.LBB0_575:
	s_add_i32 s54, s20, 2
	s_add_u32 s55, s42, 0x80
	s_addc_u32 s21, s43, 0
	s_add_i32 s74, 0, 0x10000
	s_cmp_eq_u32 s31, s20
	s_cselect_b32 s21, s51, s21
	s_cselect_b32 s20, s50, s55
	s_cselect_b32 s73, s53, s45
	s_cselect_b32 s72, s52, s44
	s_add_i32 s55, 0, 0x14000
	v_add_u32_e32 v124, s74, v207
	v_add_u32_e32 v166, s55, v207
	ds_read_b128 v[88:91], v124
	ds_read_b128 v[100:103], v124 offset:1024
	ds_read_b128 v[112:115], v124 offset:2048
	ds_read_b128 v[124:127], v124 offset:3072
	ds_read_b128 v[136:139], v166
	ds_read_b128 v[148:151], v166 offset:1024
	ds_read_b128 v[152:155], v166 offset:2048
	ds_read_b128 v[170:173], v166 offset:3072
	v_lshl_add_u64 v[166:167], s[42:43], 0, v[164:165]
	s_add_i32 m0, s61, 0xc000
	ds_read_b128 v[174:177], v211
	ds_read_b128 v[178:181], v211 offset:1024
	ds_read_b128 v[182:185], v211 offset:2048
	ds_read_b128 v[186:189], v211 offset:3072
	ds_read_b128 v[190:193], v211 offset:4096
	ds_read_b128 v[194:197], v211 offset:5120
	ds_read_b128 v[198:201], v211 offset:6144
	ds_read_b128 v[202:205], v211 offset:7168
	global_load_lds_dwordx4 v[166:167], off
	v_lshl_add_u64 v[166:167], s[42:43], 0, v[162:163]
	s_add_i32 m0, s61, 0xe000
	s_nop 0
	global_load_lds_dwordx4 v[166:167], off
	s_waitcnt vmcnt(8)
	s_waitcnt lgkmcnt(0)
	s_setprio 1
	s_barrier
	v_mfma_f32_16x16x32_bf16 v[144:147], v[88:91], v[174:177], v[144:147]
	v_mfma_f32_16x16x32_bf16 v[144:147], v[100:103], v[178:181], v[144:147]
	v_mfma_f32_16x16x32_bf16 v[140:143], v[112:115], v[174:177], v[140:143]
	v_mfma_f32_16x16x32_bf16 v[140:143], v[124:127], v[178:181], v[140:143]
	v_mfma_f32_16x16x32_bf16 v[120:123], v[88:91], v[182:185], v[120:123]
	v_mfma_f32_16x16x32_bf16 v[120:123], v[100:103], v[186:189], v[120:123]
	v_mfma_f32_16x16x32_bf16 v[116:119], v[112:115], v[182:185], v[116:119]
	v_mfma_f32_16x16x32_bf16 v[116:119], v[124:127], v[186:189], v[116:119]
	v_mfma_f32_16x16x32_bf16 v[96:99], v[88:91], v[190:193], v[96:99]
	v_mfma_f32_16x16x32_bf16 v[96:99], v[100:103], v[194:197], v[96:99]
	v_mfma_f32_16x16x32_bf16 v[92:95], v[112:115], v[190:193], v[92:95]
	v_mfma_f32_16x16x32_bf16 v[92:95], v[124:127], v[194:197], v[92:95]
	v_mfma_f32_16x16x32_bf16 v[76:79], v[88:91], v[198:201], v[76:79]
	v_mfma_f32_16x16x32_bf16 v[76:79], v[100:103], v[202:205], v[76:79]
	v_mfma_f32_16x16x32_bf16 v[72:75], v[112:115], v[198:201], v[72:75]
	v_mfma_f32_16x16x32_bf16 v[72:75], v[124:127], v[202:205], v[72:75]
	v_mfma_f32_16x16x32_bf16 v[132:135], v[136:139], v[174:177], v[132:135]
	v_mfma_f32_16x16x32_bf16 v[132:135], v[148:151], v[178:181], v[132:135]
	v_mfma_f32_16x16x32_bf16 v[128:131], v[152:155], v[174:177], v[128:131]
	v_mfma_f32_16x16x32_bf16 v[128:131], v[170:173], v[178:181], v[128:131]
	v_mfma_f32_16x16x32_bf16 v[108:111], v[136:139], v[182:185], v[108:111]
	v_mfma_f32_16x16x32_bf16 v[108:111], v[148:151], v[186:189], v[108:111]
	v_mfma_f32_16x16x32_bf16 v[104:107], v[152:155], v[182:185], v[104:107]
	v_mfma_f32_16x16x32_bf16 v[104:107], v[170:173], v[186:189], v[104:107]
	v_mfma_f32_16x16x32_bf16 v[84:87], v[136:139], v[190:193], v[84:87]
	v_mfma_f32_16x16x32_bf16 v[84:87], v[148:151], v[194:197], v[84:87]
	v_mfma_f32_16x16x32_bf16 v[80:83], v[152:155], v[190:193], v[80:83]
	v_mfma_f32_16x16x32_bf16 v[80:83], v[170:173], v[194:197], v[80:83]
	v_mfma_f32_16x16x32_bf16 v[68:71], v[136:139], v[198:201], v[68:71]
	v_mfma_f32_16x16x32_bf16 v[68:71], v[148:151], v[202:205], v[68:71]
	v_mfma_f32_16x16x32_bf16 v[64:67], v[152:155], v[198:201], v[64:67]
	v_mfma_f32_16x16x32_bf16 v[64:67], v[170:173], v[202:205], v[64:67]
	s_barrier
	s_setprio 0
	s_add_i32 s74, s74, s56
	v_lshl_add_u64 v[166:167], s[72:73], 0, v[168:169]
	s_mov_b32 m0, s74
	ds_read_b128 v[174:177], v211 offset:16384
	ds_read_b128 v[178:181], v211 offset:17408
	ds_read_b128 v[182:185], v211 offset:18432
	ds_read_b128 v[186:189], v211 offset:19456
	ds_read_b128 v[190:193], v211 offset:20480
	ds_read_b128 v[194:197], v211 offset:21504
	ds_read_b128 v[198:201], v211 offset:22528
	ds_read_b128 v[202:205], v211 offset:23552
	global_load_lds_dwordx4 v[166:167], off
	s_add_i32 m0, s74, 0x2000
	v_lshl_add_u64 v[212:213], s[72:73], 0, v[156:157]
	s_add_u32 s72, s72, s0
	s_addc_u32 s73, s73, 0
	s_add_i32 s55, s55, s56
	global_load_lds_dwordx4 v[212:213], off
	v_lshl_add_u64 v[214:215], s[72:73], 0, v[168:169]
	s_mov_b32 m0, s55
	v_lshl_add_u64 v[216:217], s[72:73], 0, v[156:157]
	global_load_lds_dwordx4 v[214:215], off
	s_add_i32 m0, s55, 0x2000
	v_lshl_add_u64 v[218:219], s[20:21], 0, v[160:161]
	global_load_lds_dwordx4 v[216:217], off
	s_mov_b32 m0, s61
	v_lshl_add_u64 v[220:221], s[20:21], 0, v[158:159]
	global_load_lds_dwordx4 v[218:219], off
	s_mov_b32 m0, s62
	s_nop 0
	global_load_lds_dwordx4 v[220:221], off
	s_waitcnt vmcnt(8)
	s_waitcnt lgkmcnt(0)
	s_setprio 1
	s_barrier
	v_mfma_f32_16x16x32_bf16 v[60:63], v[88:91], v[174:177], v[60:63]
	v_mfma_f32_16x16x32_bf16 v[60:63], v[100:103], v[178:181], v[60:63]
	v_mfma_f32_16x16x32_bf16 v[56:59], v[112:115], v[174:177], v[56:59]
	v_mfma_f32_16x16x32_bf16 v[56:59], v[124:127], v[178:181], v[56:59]
	v_mfma_f32_16x16x32_bf16 v[44:47], v[88:91], v[182:185], v[44:47]
	v_mfma_f32_16x16x32_bf16 v[44:47], v[100:103], v[186:189], v[44:47]
	v_mfma_f32_16x16x32_bf16 v[40:43], v[112:115], v[182:185], v[40:43]
	v_mfma_f32_16x16x32_bf16 v[40:43], v[124:127], v[186:189], v[40:43]
	v_mfma_f32_16x16x32_bf16 v[28:31], v[88:91], v[190:193], v[28:31]
	v_mfma_f32_16x16x32_bf16 v[28:31], v[100:103], v[194:197], v[28:31]
	v_mfma_f32_16x16x32_bf16 v[24:27], v[112:115], v[190:193], v[24:27]
	v_mfma_f32_16x16x32_bf16 v[24:27], v[124:127], v[194:197], v[24:27]
	v_mfma_f32_16x16x32_bf16 v[12:15], v[88:91], v[198:201], v[12:15]
	v_mfma_f32_16x16x32_bf16 v[12:15], v[100:103], v[202:205], v[12:15]
	v_mfma_f32_16x16x32_bf16 v[8:11], v[112:115], v[198:201], v[8:11]
	v_mfma_f32_16x16x32_bf16 v[8:11], v[124:127], v[202:205], v[8:11]
	v_mfma_f32_16x16x32_bf16 v[52:55], v[136:139], v[174:177], v[52:55]
	v_mfma_f32_16x16x32_bf16 v[52:55], v[148:151], v[178:181], v[52:55]
	v_mfma_f32_16x16x32_bf16 v[48:51], v[152:155], v[174:177], v[48:51]
	v_mfma_f32_16x16x32_bf16 v[48:51], v[170:173], v[178:181], v[48:51]
	v_mfma_f32_16x16x32_bf16 v[36:39], v[136:139], v[182:185], v[36:39]
	v_mfma_f32_16x16x32_bf16 v[36:39], v[148:151], v[186:189], v[36:39]
	v_mfma_f32_16x16x32_bf16 v[32:35], v[152:155], v[182:185], v[32:35]
	v_mfma_f32_16x16x32_bf16 v[32:35], v[170:173], v[186:189], v[32:35]
	v_mfma_f32_16x16x32_bf16 v[20:23], v[136:139], v[190:193], v[20:23]
	v_mfma_f32_16x16x32_bf16 v[20:23], v[148:151], v[194:197], v[20:23]
	v_mfma_f32_16x16x32_bf16 v[16:19], v[152:155], v[190:193], v[16:19]
	v_mfma_f32_16x16x32_bf16 v[16:19], v[170:173], v[194:197], v[16:19]
	v_mfma_f32_16x16x32_bf16 v[4:7], v[136:139], v[198:201], v[4:7]
	v_mfma_f32_16x16x32_bf16 v[4:7], v[148:151], v[202:205], v[4:7]
	v_mfma_f32_16x16x32_bf16 v[0:3], v[152:155], v[198:201], v[0:3]
	v_mfma_f32_16x16x32_bf16 v[0:3], v[170:173], v[202:205], v[0:3]
	s_barrier
	s_setprio 0
	s_add_i32 s55, 0, 0x18000
	s_add_i32 s72, 0, 0x1c000
	v_add_u32_e32 v124, s55, v207
	v_add_u32_e32 v170, s72, v207
	ds_read_b128 v[88:91], v124
	ds_read_b128 v[100:103], v124 offset:1024
	ds_read_b128 v[112:115], v124 offset:2048
	ds_read_b128 v[124:127], v124 offset:3072
	ds_read_b128 v[136:139], v170
	ds_read_b128 v[148:151], v170 offset:1024
	ds_read_b128 v[152:155], v170 offset:2048
	ds_read_b128 v[170:173], v170 offset:3072
	s_add_u32 s20, s20, s0
	s_addc_u32 s21, s21, 0
	s_mov_b32 m0, s63
	v_lshl_add_u64 v[222:223], s[20:21], 0, v[160:161]
	ds_read_b128 v[174:177], v211 offset:32768
	ds_read_b128 v[178:181], v211 offset:33792
	ds_read_b128 v[182:185], v211 offset:34816
	ds_read_b128 v[186:189], v211 offset:35840
	ds_read_b128 v[190:193], v211 offset:36864
	ds_read_b128 v[194:197], v211 offset:37888
	ds_read_b128 v[198:201], v211 offset:38912
	ds_read_b128 v[202:205], v211 offset:39936
	global_load_lds_dwordx4 v[222:223], off
	v_lshl_add_u64 v[222:223], s[20:21], 0, v[158:159]
	s_mov_b32 m0, s64
	s_nop 0
	global_load_lds_dwordx4 v[222:223], off
	s_waitcnt vmcnt(8)
	s_waitcnt lgkmcnt(0)
	s_setprio 1
	s_barrier
	v_mfma_f32_16x16x32_bf16 v[144:147], v[88:91], v[174:177], v[144:147]
	v_mfma_f32_16x16x32_bf16 v[144:147], v[100:103], v[178:181], v[144:147]
	v_mfma_f32_16x16x32_bf16 v[140:143], v[112:115], v[174:177], v[140:143]
	v_mfma_f32_16x16x32_bf16 v[140:143], v[124:127], v[178:181], v[140:143]
	v_mfma_f32_16x16x32_bf16 v[120:123], v[88:91], v[182:185], v[120:123]
	v_mfma_f32_16x16x32_bf16 v[120:123], v[100:103], v[186:189], v[120:123]
	v_mfma_f32_16x16x32_bf16 v[116:119], v[112:115], v[182:185], v[116:119]
	v_mfma_f32_16x16x32_bf16 v[116:119], v[124:127], v[186:189], v[116:119]
	v_mfma_f32_16x16x32_bf16 v[96:99], v[88:91], v[190:193], v[96:99]
	v_mfma_f32_16x16x32_bf16 v[96:99], v[100:103], v[194:197], v[96:99]
	v_mfma_f32_16x16x32_bf16 v[92:95], v[112:115], v[190:193], v[92:95]
	v_mfma_f32_16x16x32_bf16 v[92:95], v[124:127], v[194:197], v[92:95]
	v_mfma_f32_16x16x32_bf16 v[76:79], v[88:91], v[198:201], v[76:79]
	v_mfma_f32_16x16x32_bf16 v[76:79], v[100:103], v[202:205], v[76:79]
	v_mfma_f32_16x16x32_bf16 v[72:75], v[112:115], v[198:201], v[72:75]
	v_mfma_f32_16x16x32_bf16 v[72:75], v[124:127], v[202:205], v[72:75]
	v_mfma_f32_16x16x32_bf16 v[132:135], v[136:139], v[174:177], v[132:135]
	v_mfma_f32_16x16x32_bf16 v[132:135], v[148:151], v[178:181], v[132:135]
	v_mfma_f32_16x16x32_bf16 v[128:131], v[152:155], v[174:177], v[128:131]
	v_mfma_f32_16x16x32_bf16 v[128:131], v[170:173], v[178:181], v[128:131]
	v_mfma_f32_16x16x32_bf16 v[108:111], v[136:139], v[182:185], v[108:111]
	v_mfma_f32_16x16x32_bf16 v[108:111], v[148:151], v[186:189], v[108:111]
	v_mfma_f32_16x16x32_bf16 v[104:107], v[152:155], v[182:185], v[104:107]
	v_mfma_f32_16x16x32_bf16 v[104:107], v[170:173], v[186:189], v[104:107]
	v_mfma_f32_16x16x32_bf16 v[84:87], v[136:139], v[190:193], v[84:87]
	v_mfma_f32_16x16x32_bf16 v[84:87], v[148:151], v[194:197], v[84:87]
	v_mfma_f32_16x16x32_bf16 v[80:83], v[152:155], v[190:193], v[80:83]
	v_mfma_f32_16x16x32_bf16 v[80:83], v[170:173], v[194:197], v[80:83]
	v_mfma_f32_16x16x32_bf16 v[68:71], v[136:139], v[198:201], v[68:71]
	v_mfma_f32_16x16x32_bf16 v[68:71], v[148:151], v[202:205], v[68:71]
	v_mfma_f32_16x16x32_bf16 v[64:67], v[152:155], v[198:201], v[64:67]
	v_mfma_f32_16x16x32_bf16 v[64:67], v[170:173], v[202:205], v[64:67]
	s_barrier
	s_setprio 0
	s_add_i32 s20, s55, s56
	v_lshl_add_u64 v[166:167], v[166:167], 0, s[36:37]
	s_mov_b32 m0, s20
	ds_read_b128 v[174:177], v211 offset:49152
	ds_read_b128 v[178:181], v211 offset:50176
	ds_read_b128 v[182:185], v211 offset:51200
	ds_read_b128 v[186:189], v211 offset:52224
	ds_read_b128 v[190:193], v211 offset:53248
	ds_read_b128 v[194:197], v211 offset:54272
	ds_read_b128 v[198:201], v211 offset:55296
	ds_read_b128 v[202:205], v211 offset:56320
	global_load_lds_dwordx4 v[166:167], off
	v_lshl_add_u64 v[166:167], v[212:213], 0, s[36:37]
	s_add_i32 m0, s20, 0x2000
	s_add_i32 s20, s72, s56
	global_load_lds_dwordx4 v[166:167], off
	v_lshl_add_u64 v[166:167], v[214:215], 0, s[36:37]
	s_mov_b32 m0, s20
	s_nop 0
	global_load_lds_dwordx4 v[166:167], off
	v_lshl_add_u64 v[166:167], v[216:217], 0, s[36:37]
	s_add_i32 m0, s20, 0x2000
	s_nop 0
	global_load_lds_dwordx4 v[166:167], off
	v_lshl_add_u64 v[166:167], v[218:219], 0, s[36:37]
	s_mov_b32 m0, s66
	s_nop 0
	global_load_lds_dwordx4 v[166:167], off
	v_lshl_add_u64 v[166:167], v[220:221], 0, s[36:37]
	s_mov_b32 m0, s67
	s_nop 0
	global_load_lds_dwordx4 v[166:167], off
	s_waitcnt vmcnt(8)
	s_waitcnt lgkmcnt(0)
	s_setprio 1
	s_barrier
	v_mfma_f32_16x16x32_bf16 v[60:63], v[88:91], v[174:177], v[60:63]
	v_mfma_f32_16x16x32_bf16 v[60:63], v[100:103], v[178:181], v[60:63]
	v_mfma_f32_16x16x32_bf16 v[56:59], v[112:115], v[174:177], v[56:59]
	v_mfma_f32_16x16x32_bf16 v[56:59], v[124:127], v[178:181], v[56:59]
	v_mfma_f32_16x16x32_bf16 v[44:47], v[88:91], v[182:185], v[44:47]
	v_mfma_f32_16x16x32_bf16 v[44:47], v[100:103], v[186:189], v[44:47]
	v_mfma_f32_16x16x32_bf16 v[40:43], v[112:115], v[182:185], v[40:43]
	v_mfma_f32_16x16x32_bf16 v[40:43], v[124:127], v[186:189], v[40:43]
	v_mfma_f32_16x16x32_bf16 v[28:31], v[88:91], v[190:193], v[28:31]
	v_mfma_f32_16x16x32_bf16 v[28:31], v[100:103], v[194:197], v[28:31]
	v_mfma_f32_16x16x32_bf16 v[24:27], v[112:115], v[190:193], v[24:27]
	v_mfma_f32_16x16x32_bf16 v[24:27], v[124:127], v[194:197], v[24:27]
	v_mfma_f32_16x16x32_bf16 v[12:15], v[88:91], v[198:201], v[12:15]
	v_mfma_f32_16x16x32_bf16 v[12:15], v[100:103], v[202:205], v[12:15]
	v_mfma_f32_16x16x32_bf16 v[8:11], v[112:115], v[198:201], v[8:11]
	v_mfma_f32_16x16x32_bf16 v[8:11], v[124:127], v[202:205], v[8:11]
	v_mfma_f32_16x16x32_bf16 v[52:55], v[136:139], v[174:177], v[52:55]
	v_mfma_f32_16x16x32_bf16 v[52:55], v[148:151], v[178:181], v[52:55]
	v_mfma_f32_16x16x32_bf16 v[48:51], v[152:155], v[174:177], v[48:51]
	v_mfma_f32_16x16x32_bf16 v[48:51], v[170:173], v[178:181], v[48:51]
	v_mfma_f32_16x16x32_bf16 v[36:39], v[136:139], v[182:185], v[36:39]
	v_mfma_f32_16x16x32_bf16 v[36:39], v[148:151], v[186:189], v[36:39]
	v_mfma_f32_16x16x32_bf16 v[32:35], v[152:155], v[182:185], v[32:35]
	v_mfma_f32_16x16x32_bf16 v[32:35], v[170:173], v[186:189], v[32:35]
	v_mfma_f32_16x16x32_bf16 v[20:23], v[136:139], v[190:193], v[20:23]
	v_mfma_f32_16x16x32_bf16 v[20:23], v[148:151], v[194:197], v[20:23]
	v_mfma_f32_16x16x32_bf16 v[16:19], v[152:155], v[190:193], v[16:19]
	v_mfma_f32_16x16x32_bf16 v[16:19], v[170:173], v[194:197], v[16:19]
	v_mfma_f32_16x16x32_bf16 v[4:7], v[136:139], v[198:201], v[4:7]
	v_mfma_f32_16x16x32_bf16 v[4:7], v[148:151], v[202:205], v[4:7]
	v_mfma_f32_16x16x32_bf16 v[0:3], v[152:155], v[198:201], v[0:3]
	v_mfma_f32_16x16x32_bf16 v[0:3], v[170:173], v[202:205], v[0:3]
	s_barrier
	s_setprio 0
	s_add_u32 s44, s44, 0x100
	s_addc_u32 s45, s45, 0
	s_add_u32 s42, s42, 0x100
	s_addc_u32 s43, s43, 0
	s_cmp_ge_u32 s54, s3
	s_mov_b32 s20, s54
	s_cbranch_scc0 .LBB0_575
	s_and_b64 vcc, exec, s[16:17]
	s_cbranch_vccz .LBB0_578
	s_barrier

.LBB0_692:
	s_add_u32 s20, s40, 0xfffc0080
	s_addc_u32 s21, s41, -1
	s_add_i32 s71, 0, 0x10000
	s_cmp_eq_u32 s70, 12
	s_cselect_b32 s51, s43, s21
	s_cselect_b32 s50, s66, s20
	s_cselect_b32 s21, s19, s69
	s_cselect_b32 s20, s67, s68
	s_add_i32 s74, 0, 0x14000
	v_add_u32_e32 v150, s71, v156
	v_add_u32_e32 v188, s74, v156
	ds_read_b128 v[138:141], v150
	ds_read_b128 v[142:145], v150 offset:1024
	ds_read_b128 v[146:149], v150 offset:2048
	ds_read_b128 v[150:153], v150 offset:3072
	ds_read_b128 v[176:179], v188
	ds_read_b128 v[180:183], v188 offset:1024
	ds_read_b128 v[184:187], v188 offset:2048
	ds_read_b128 v[188:191], v188 offset:3072
	v_lshl_add_u64 v[224:225], s[40:41], 0, v[136:137]
	s_add_i32 m0, s57, 0xc000
	ds_read_b128 v[192:195], v175
	ds_read_b128 v[196:199], v175 offset:1024
	ds_read_b128 v[200:203], v175 offset:2048
	ds_read_b128 v[204:207], v175 offset:3072
	ds_read_b128 v[208:211], v175 offset:4096
	ds_read_b128 v[212:215], v175 offset:5120
	ds_read_b128 v[216:219], v175 offset:6144
	ds_read_b128 v[220:223], v175 offset:7168
	global_load_lds_dwordx4 v[224:225], off
	v_lshl_add_u64 v[224:225], s[40:41], 0, v[134:135]
	s_add_i32 m0, s57, 0xe000
	s_nop 0
	global_load_lds_dwordx4 v[224:225], off
	s_waitcnt vmcnt(8)
	s_waitcnt lgkmcnt(0)
	s_setprio 1
	s_barrier
	v_mfma_f32_16x16x32_bf16 v[124:127], v[138:141], v[192:195], v[124:127]
	v_mfma_f32_16x16x32_bf16 v[124:127], v[142:145], v[196:199], v[124:127]
	v_mfma_f32_16x16x32_bf16 v[112:115], v[146:149], v[192:195], v[112:115]
	v_mfma_f32_16x16x32_bf16 v[112:115], v[150:153], v[196:199], v[112:115]
	v_mfma_f32_16x16x32_bf16 v[108:111], v[138:141], v[200:203], v[108:111]
	v_mfma_f32_16x16x32_bf16 v[108:111], v[142:145], v[204:207], v[108:111]
	v_mfma_f32_16x16x32_bf16 v[96:99], v[146:149], v[200:203], v[96:99]
	v_mfma_f32_16x16x32_bf16 v[96:99], v[150:153], v[204:207], v[96:99]
	v_mfma_f32_16x16x32_bf16 v[92:95], v[138:141], v[208:211], v[92:95]
	v_mfma_f32_16x16x32_bf16 v[92:95], v[142:145], v[212:215], v[92:95]
	v_mfma_f32_16x16x32_bf16 v[80:83], v[146:149], v[208:211], v[80:83]
	v_mfma_f32_16x16x32_bf16 v[80:83], v[150:153], v[212:215], v[80:83]
	v_mfma_f32_16x16x32_bf16 v[76:79], v[138:141], v[216:219], v[76:79]
	v_mfma_f32_16x16x32_bf16 v[76:79], v[142:145], v[220:223], v[76:79]
	v_mfma_f32_16x16x32_bf16 v[64:67], v[146:149], v[216:219], v[64:67]
	v_mfma_f32_16x16x32_bf16 v[64:67], v[150:153], v[220:223], v[64:67]
	v_mfma_f32_16x16x32_bf16 v[120:123], v[176:179], v[192:195], v[120:123]
	v_mfma_f32_16x16x32_bf16 v[120:123], v[180:183], v[196:199], v[120:123]
	v_mfma_f32_16x16x32_bf16 v[116:119], v[184:187], v[192:195], v[116:119]
	v_mfma_f32_16x16x32_bf16 v[116:119], v[188:191], v[196:199], v[116:119]
	v_mfma_f32_16x16x32_bf16 v[104:107], v[176:179], v[200:203], v[104:107]
	v_mfma_f32_16x16x32_bf16 v[104:107], v[180:183], v[204:207], v[104:107]
	v_mfma_f32_16x16x32_bf16 v[100:103], v[184:187], v[200:203], v[100:103]
	v_mfma_f32_16x16x32_bf16 v[100:103], v[188:191], v[204:207], v[100:103]
	v_mfma_f32_16x16x32_bf16 v[88:91], v[176:179], v[208:211], v[88:91]
	v_mfma_f32_16x16x32_bf16 v[88:91], v[180:183], v[212:215], v[88:91]
	v_mfma_f32_16x16x32_bf16 v[84:87], v[184:187], v[208:211], v[84:87]
	v_mfma_f32_16x16x32_bf16 v[84:87], v[188:191], v[212:215], v[84:87]
	v_mfma_f32_16x16x32_bf16 v[72:75], v[176:179], v[216:219], v[72:75]
	v_mfma_f32_16x16x32_bf16 v[72:75], v[180:183], v[220:223], v[72:75]
	v_mfma_f32_16x16x32_bf16 v[68:71], v[184:187], v[216:219], v[68:71]
	v_mfma_f32_16x16x32_bf16 v[68:71], v[188:191], v[220:223], v[68:71]
	s_barrier
	s_setprio 0
	s_add_i32 s71, s71, s54
	v_lshl_add_u64 v[224:225], s[20:21], 0, v[168:169]
	s_mov_b32 m0, s71
	ds_read_b128 v[192:195], v175 offset:16384
	ds_read_b128 v[196:199], v175 offset:17408
	ds_read_b128 v[200:203], v175 offset:18432
	ds_read_b128 v[204:207], v175 offset:19456
	ds_read_b128 v[208:211], v175 offset:20480
	ds_read_b128 v[212:215], v175 offset:21504
	ds_read_b128 v[216:219], v175 offset:22528
	ds_read_b128 v[220:223], v175 offset:23552
	global_load_lds_dwordx4 v[224:225], off
	s_add_i32 m0, s71, 0x2000
	s_add_u32 s72, s20, 0x40000
	v_lshl_add_u64 v[226:227], s[20:21], 0, v[128:129]
	s_addc_u32 s73, s21, 0
	s_add_i32 s71, s74, s54
	global_load_lds_dwordx4 v[226:227], off
	v_lshl_add_u64 v[228:229], s[72:73], 0, v[168:169]
	s_mov_b32 m0, s71
	v_lshl_add_u64 v[230:231], s[50:51], 0, v[130:131]
	global_load_lds_dwordx4 v[228:229], off
	v_lshl_add_u64 v[228:229], s[72:73], 0, v[128:129]
	s_add_i32 m0, s71, 0x2000
	s_nop 0
	global_load_lds_dwordx4 v[228:229], off
	v_lshl_add_u64 v[228:229], s[50:51], 0, v[132:133]
	s_mov_b32 m0, s57
	s_nop 0
	global_load_lds_dwordx4 v[228:229], off
	s_mov_b32 m0, s58
	s_nop 0
	global_load_lds_dwordx4 v[230:231], off
	s_waitcnt vmcnt(8)
	s_waitcnt lgkmcnt(0)
	s_setprio 1
	s_barrier
	v_mfma_f32_16x16x32_bf16 v[60:63], v[138:141], v[192:195], v[60:63]
	v_mfma_f32_16x16x32_bf16 v[60:63], v[142:145], v[196:199], v[60:63]
	v_mfma_f32_16x16x32_bf16 v[48:51], v[146:149], v[192:195], v[48:51]
	v_mfma_f32_16x16x32_bf16 v[48:51], v[150:153], v[196:199], v[48:51]
	v_mfma_f32_16x16x32_bf16 v[44:47], v[138:141], v[200:203], v[44:47]
	v_mfma_f32_16x16x32_bf16 v[44:47], v[142:145], v[204:207], v[44:47]
	v_mfma_f32_16x16x32_bf16 v[32:35], v[146:149], v[200:203], v[32:35]
	v_mfma_f32_16x16x32_bf16 v[32:35], v[150:153], v[204:207], v[32:35]
	v_mfma_f32_16x16x32_bf16 v[28:31], v[138:141], v[208:211], v[28:31]
	v_mfma_f32_16x16x32_bf16 v[28:31], v[142:145], v[212:215], v[28:31]
	v_mfma_f32_16x16x32_bf16 v[16:19], v[146:149], v[208:211], v[16:19]
	v_mfma_f32_16x16x32_bf16 v[16:19], v[150:153], v[212:215], v[16:19]
	v_mfma_f32_16x16x32_bf16 v[12:15], v[138:141], v[216:219], v[12:15]
	v_mfma_f32_16x16x32_bf16 v[12:15], v[142:145], v[220:223], v[12:15]
	v_mfma_f32_16x16x32_bf16 v[4:7], v[146:149], v[216:219], v[4:7]
	v_mfma_f32_16x16x32_bf16 v[4:7], v[150:153], v[220:223], v[4:7]
	v_mfma_f32_16x16x32_bf16 v[56:59], v[176:179], v[192:195], v[56:59]
	v_mfma_f32_16x16x32_bf16 v[56:59], v[180:183], v[196:199], v[56:59]
	v_mfma_f32_16x16x32_bf16 v[52:55], v[184:187], v[192:195], v[52:55]
	v_mfma_f32_16x16x32_bf16 v[52:55], v[188:191], v[196:199], v[52:55]
	v_mfma_f32_16x16x32_bf16 v[40:43], v[176:179], v[200:203], v[40:43]
	v_mfma_f32_16x16x32_bf16 v[40:43], v[180:183], v[204:207], v[40:43]
	v_mfma_f32_16x16x32_bf16 v[36:39], v[184:187], v[200:203], v[36:39]
	v_mfma_f32_16x16x32_bf16 v[36:39], v[188:191], v[204:207], v[36:39]
	v_mfma_f32_16x16x32_bf16 v[24:27], v[176:179], v[208:211], v[24:27]
	v_mfma_f32_16x16x32_bf16 v[24:27], v[180:183], v[212:215], v[24:27]
	v_mfma_f32_16x16x32_bf16 v[20:23], v[184:187], v[208:211], v[20:23]
	v_mfma_f32_16x16x32_bf16 v[20:23], v[188:191], v[212:215], v[20:23]
	v_mfma_f32_16x16x32_bf16 v[8:11], v[176:179], v[216:219], v[8:11]
	v_mfma_f32_16x16x32_bf16 v[8:11], v[180:183], v[220:223], v[8:11]
	v_mfma_f32_16x16x32_bf16 v[0:3], v[184:187], v[216:219], v[0:3]
	v_mfma_f32_16x16x32_bf16 v[0:3], v[188:191], v[220:223], v[0:3]
	s_barrier
	s_setprio 0
	s_add_i32 s71, 0, 0x18000
	s_add_i32 s72, 0, 0x1c000
	v_add_u32_e32 v150, s71, v156
	v_add_u32_e32 v188, s72, v156
	ds_read_b128 v[138:141], v150
	ds_read_b128 v[142:145], v150 offset:1024
	ds_read_b128 v[146:149], v150 offset:2048
	ds_read_b128 v[150:153], v150 offset:3072
	ds_read_b128 v[176:179], v188
	ds_read_b128 v[180:183], v188 offset:1024
	ds_read_b128 v[184:187], v188 offset:2048
	ds_read_b128 v[188:191], v188 offset:3072
	s_add_u32 s50, s50, 0x40000
	s_addc_u32 s51, s51, 0
	s_mov_b32 m0, s59
	v_lshl_add_u64 v[232:233], s[50:51], 0, v[132:133]
	ds_read_b128 v[192:195], v175 offset:32768
	ds_read_b128 v[196:199], v175 offset:33792
	ds_read_b128 v[200:203], v175 offset:34816
	ds_read_b128 v[204:207], v175 offset:35840
	ds_read_b128 v[208:211], v175 offset:36864
	ds_read_b128 v[212:215], v175 offset:37888
	ds_read_b128 v[216:219], v175 offset:38912
	ds_read_b128 v[220:223], v175 offset:39936
	global_load_lds_dwordx4 v[232:233], off
	v_lshl_add_u64 v[232:233], s[50:51], 0, v[130:131]
	s_mov_b32 m0, s60
	s_nop 0
	global_load_lds_dwordx4 v[232:233], off
	s_waitcnt vmcnt(8)
	s_waitcnt lgkmcnt(0)
	s_setprio 1
	s_barrier
	v_mfma_f32_16x16x32_bf16 v[124:127], v[138:141], v[192:195], v[124:127]
	v_mfma_f32_16x16x32_bf16 v[124:127], v[142:145], v[196:199], v[124:127]
	v_mfma_f32_16x16x32_bf16 v[112:115], v[146:149], v[192:195], v[112:115]
	v_mfma_f32_16x16x32_bf16 v[112:115], v[150:153], v[196:199], v[112:115]
	v_mfma_f32_16x16x32_bf16 v[108:111], v[138:141], v[200:203], v[108:111]
	v_mfma_f32_16x16x32_bf16 v[108:111], v[142:145], v[204:207], v[108:111]
	v_mfma_f32_16x16x32_bf16 v[96:99], v[146:149], v[200:203], v[96:99]
	v_mfma_f32_16x16x32_bf16 v[96:99], v[150:153], v[204:207], v[96:99]
	v_mfma_f32_16x16x32_bf16 v[92:95], v[138:141], v[208:211], v[92:95]
	v_mfma_f32_16x16x32_bf16 v[92:95], v[142:145], v[212:215], v[92:95]
	v_mfma_f32_16x16x32_bf16 v[80:83], v[146:149], v[208:211], v[80:83]
	v_mfma_f32_16x16x32_bf16 v[80:83], v[150:153], v[212:215], v[80:83]
	v_mfma_f32_16x16x32_bf16 v[76:79], v[138:141], v[216:219], v[76:79]
	v_mfma_f32_16x16x32_bf16 v[76:79], v[142:145], v[220:223], v[76:79]
	v_mfma_f32_16x16x32_bf16 v[64:67], v[146:149], v[216:219], v[64:67]
	v_mfma_f32_16x16x32_bf16 v[64:67], v[150:153], v[220:223], v[64:67]
	v_mfma_f32_16x16x32_bf16 v[120:123], v[176:179], v[192:195], v[120:123]
	v_mfma_f32_16x16x32_bf16 v[120:123], v[180:183], v[196:199], v[120:123]
	v_mfma_f32_16x16x32_bf16 v[116:119], v[184:187], v[192:195], v[116:119]
	v_mfma_f32_16x16x32_bf16 v[116:119], v[188:191], v[196:199], v[116:119]
	v_mfma_f32_16x16x32_bf16 v[104:107], v[176:179], v[200:203], v[104:107]
	v_mfma_f32_16x16x32_bf16 v[104:107], v[180:183], v[204:207], v[104:107]
	v_mfma_f32_16x16x32_bf16 v[100:103], v[184:187], v[200:203], v[100:103]
	v_mfma_f32_16x16x32_bf16 v[100:103], v[188:191], v[204:207], v[100:103]
	v_mfma_f32_16x16x32_bf16 v[88:91], v[176:179], v[208:211], v[88:91]
	v_mfma_f32_16x16x32_bf16 v[88:91], v[180:183], v[212:215], v[88:91]
	v_mfma_f32_16x16x32_bf16 v[84:87], v[184:187], v[208:211], v[84:87]
	v_mfma_f32_16x16x32_bf16 v[84:87], v[188:191], v[212:215], v[84:87]
	v_mfma_f32_16x16x32_bf16 v[72:75], v[176:179], v[216:219], v[72:75]
	v_mfma_f32_16x16x32_bf16 v[72:75], v[180:183], v[220:223], v[72:75]
	v_mfma_f32_16x16x32_bf16 v[68:71], v[184:187], v[216:219], v[68:71]
	v_mfma_f32_16x16x32_bf16 v[68:71], v[188:191], v[220:223], v[68:71]
	s_barrier
	s_setprio 0
	s_add_i32 s50, s71, s54
	v_lshl_add_u64 v[224:225], v[224:225], 0, s[36:37]
	s_mov_b32 m0, s50
	ds_read_b128 v[192:195], v175 offset:49152
	ds_read_b128 v[196:199], v175 offset:50176
	ds_read_b128 v[200:203], v175 offset:51200
	ds_read_b128 v[204:207], v175 offset:52224
	ds_read_b128 v[208:211], v175 offset:53248
	ds_read_b128 v[212:215], v175 offset:54272
	ds_read_b128 v[216:219], v175 offset:55296
	ds_read_b128 v[220:223], v175 offset:56320
	global_load_lds_dwordx4 v[224:225], off
	s_add_i32 m0, s50, 0x2000
	s_add_u32 s20, s20, 0x40080
	v_lshl_add_u64 v[224:225], v[226:227], 0, s[36:37]
	s_addc_u32 s21, s21, 0
	s_add_i32 s50, s72, s54
	global_load_lds_dwordx4 v[224:225], off
	v_lshl_add_u64 v[224:225], s[20:21], 0, v[168:169]
	s_mov_b32 m0, s50
	s_nop 0
	global_load_lds_dwordx4 v[224:225], off
	v_lshl_add_u64 v[224:225], s[20:21], 0, v[128:129]
	s_add_i32 m0, s50, 0x2000
	s_nop 0
	global_load_lds_dwordx4 v[224:225], off
	v_lshl_add_u64 v[224:225], v[228:229], 0, s[36:37]
	s_mov_b32 m0, s61
	s_nop 0
	global_load_lds_dwordx4 v[224:225], off
	v_lshl_add_u64 v[224:225], v[230:231], 0, s[36:37]
	s_mov_b32 m0, s62
	s_nop 0
	global_load_lds_dwordx4 v[224:225], off
	s_waitcnt vmcnt(8)
	s_waitcnt lgkmcnt(0)
	s_setprio 1
	s_barrier
	v_mfma_f32_16x16x32_bf16 v[60:63], v[138:141], v[192:195], v[60:63]
	v_mfma_f32_16x16x32_bf16 v[60:63], v[142:145], v[196:199], v[60:63]
	v_mfma_f32_16x16x32_bf16 v[48:51], v[146:149], v[192:195], v[48:51]
	v_mfma_f32_16x16x32_bf16 v[48:51], v[150:153], v[196:199], v[48:51]
	v_mfma_f32_16x16x32_bf16 v[44:47], v[138:141], v[200:203], v[44:47]
	v_mfma_f32_16x16x32_bf16 v[44:47], v[142:145], v[204:207], v[44:47]
	v_mfma_f32_16x16x32_bf16 v[32:35], v[146:149], v[200:203], v[32:35]
	v_mfma_f32_16x16x32_bf16 v[32:35], v[150:153], v[204:207], v[32:35]
	v_mfma_f32_16x16x32_bf16 v[28:31], v[138:141], v[208:211], v[28:31]
	v_mfma_f32_16x16x32_bf16 v[28:31], v[142:145], v[212:215], v[28:31]
	v_mfma_f32_16x16x32_bf16 v[16:19], v[146:149], v[208:211], v[16:19]
	v_mfma_f32_16x16x32_bf16 v[16:19], v[150:153], v[212:215], v[16:19]
	v_mfma_f32_16x16x32_bf16 v[12:15], v[138:141], v[216:219], v[12:15]
	v_mfma_f32_16x16x32_bf16 v[12:15], v[142:145], v[220:223], v[12:15]
	v_mfma_f32_16x16x32_bf16 v[4:7], v[146:149], v[216:219], v[4:7]
	v_mfma_f32_16x16x32_bf16 v[4:7], v[150:153], v[220:223], v[4:7]
	v_mfma_f32_16x16x32_bf16 v[56:59], v[176:179], v[192:195], v[56:59]
	v_mfma_f32_16x16x32_bf16 v[56:59], v[180:183], v[196:199], v[56:59]
	v_mfma_f32_16x16x32_bf16 v[52:55], v[184:187], v[192:195], v[52:55]
	v_mfma_f32_16x16x32_bf16 v[52:55], v[188:191], v[196:199], v[52:55]
	v_mfma_f32_16x16x32_bf16 v[40:43], v[176:179], v[200:203], v[40:43]
	v_mfma_f32_16x16x32_bf16 v[40:43], v[180:183], v[204:207], v[40:43]
	v_mfma_f32_16x16x32_bf16 v[36:39], v[184:187], v[200:203], v[36:39]
	v_mfma_f32_16x16x32_bf16 v[36:39], v[188:191], v[204:207], v[36:39]
	v_mfma_f32_16x16x32_bf16 v[24:27], v[176:179], v[208:211], v[24:27]
	v_mfma_f32_16x16x32_bf16 v[24:27], v[180:183], v[212:215], v[24:27]
	v_mfma_f32_16x16x32_bf16 v[20:23], v[184:187], v[208:211], v[20:23]
	v_mfma_f32_16x16x32_bf16 v[20:23], v[188:191], v[212:215], v[20:23]
	v_mfma_f32_16x16x32_bf16 v[8:11], v[176:179], v[216:219], v[8:11]
	v_mfma_f32_16x16x32_bf16 v[8:11], v[180:183], v[220:223], v[8:11]
	v_mfma_f32_16x16x32_bf16 v[0:3], v[184:187], v[216:219], v[0:3]
	v_mfma_f32_16x16x32_bf16 v[0:3], v[188:191], v[220:223], v[0:3]
	s_barrier
	s_setprio 0
	s_add_i32 s70, s70, 2
	s_add_u32 s68, s68, 0x100
	s_addc_u32 s69, s69, 0
	s_add_u32 s40, s40, 0x100
	s_addc_u32 s41, s41, 0
	s_cmp_gt_u32 s70, 13
	s_cbranch_scc0 .LBB0_692
	s_and_b64 vcc, exec, s[16:17]
	s_cbranch_vccz .LBB0_695
	s_barrier
